# v114: v106 with write-through (sc1) x stores also in the plain (un-folded) residual epilogue of the two remaining residual steps
# speedup vs baseline: 1.0110x; 1.0110x over previous
.Lres_nobias:
	s_nop 2
	global_load_dwordx4 v[216:219], v250, s[8:9] offset:0
	global_load_dwordx4 v[220:223], v250, s[8:9] offset:64
	global_load_dwordx4 v[240:243], v250, s[8:9] offset:512
	global_load_dwordx4 v[244:247], v250, s[8:9] offset:576
	v_readlane_b32 s3, v254, 61
	s_mov_b32 s2, -1
	s_cmp_eq_u32 s3, 8
	s_cselect_b32 s2, 2, s2
	s_cmp_eq_u32 s3, 10
	s_cselect_b32 s2, 4, s2
	s_cmp_eq_u32 s3, 17
	s_cselect_b32 s2, 6, s2
	s_cmp_eq_u32 s3, 19
	s_cselect_b32 s2, 8, s2
	s_cmp_eq_u32 s3, 21
	s_cselect_b32 s2, 9, s2
	s_cmp_eq_u32 s3, 25
	s_cselect_b32 s2, 10, s2
	s_cmp_eq_u32 s3, 27
	s_cselect_b32 s2, 12, s2
	s_cmp_eq_u32 s3, 29
	s_cselect_b32 s2, 13, s2
	s_cmp_eq_u32 s3, 32
	s_cselect_b32 s2, 14, s2
	s_cmp_eq_u32 s3, 34
	s_cselect_b32 s2, 99, s2
	s_mov_b32 s100, s2
	s_cmp_lt_i32 s2, 0
	s_cbranch_scc0 .Lrf_fused
	global_load_dwordx4 v[130:133], v248, s[10:11] offset:0
	s_add_u32 s14, s10, 0x10000
	s_addc_u32 s15, s11, 0
	global_load_dwordx4 v[134:137], v248, s[14:15] offset:0
	s_add_u32 s14, s10, 0x20000
	s_addc_u32 s15, s11, 0
	global_load_dwordx4 v[138:141], v248, s[14:15] offset:0
	s_add_u32 s14, s10, 0x30000
	s_addc_u32 s15, s11, 0
	global_load_dwordx4 v[142:145], v248, s[14:15] offset:0
	s_add_u32 s14, s10, 0x80000
	s_addc_u32 s15, s11, 0
	global_load_dwordx4 v[146:149], v248, s[14:15] offset:0
	s_add_u32 s14, s10, 0x90000
	s_addc_u32 s15, s11, 0
	global_load_dwordx4 v[150:153], v248, s[14:15] offset:0
	s_add_u32 s14, s10, 0xa0000
	s_addc_u32 s15, s11, 0
	global_load_dwordx4 v[154:157], v248, s[14:15] offset:0
	s_add_u32 s14, s10, 0xb0000
	s_addc_u32 s15, s11, 0
	global_load_dwordx4 v[158:161], v248, s[14:15] offset:0
	global_load_dwordx4 v[162:165], v248, s[10:11] offset:64
	s_add_u32 s14, s10, 0x10000
	s_addc_u32 s15, s11, 0
	global_load_dwordx4 v[188:191], v248, s[14:15] offset:64
	s_add_u32 s14, s10, 0x20000
	s_addc_u32 s15, s11, 0
	global_load_dwordx4 v[192:195], v248, s[14:15] offset:64
	s_add_u32 s14, s10, 0x30000
	s_addc_u32 s15, s11, 0
	global_load_dwordx4 v[196:199], v248, s[14:15] offset:64
	s_add_u32 s14, s10, 0x80000
	s_addc_u32 s15, s11, 0
	global_load_dwordx4 v[200:203], v248, s[14:15] offset:64
	s_add_u32 s14, s10, 0x90000
	s_addc_u32 s15, s11, 0
	global_load_dwordx4 v[204:207], v248, s[14:15] offset:64
	s_add_u32 s14, s10, 0xa0000
	s_addc_u32 s15, s11, 0
	global_load_dwordx4 v[208:211], v248, s[14:15] offset:64
	s_add_u32 s14, s10, 0xb0000
	s_addc_u32 s15, s11, 0
	global_load_dwordx4 v[212:215], v248, s[14:15] offset:64
	s_waitcnt vmcnt(12)
	v_pk_mul_f32 v[216:217], s[28:29], v[216:217]
	v_pk_mul_f32 v[218:219], s[28:29], v[218:219]
	v_pk_mul_f32 v[220:221], s[28:29], v[220:221]
	v_pk_mul_f32 v[222:223], s[28:29], v[222:223]
	v_pk_mul_f32 v[240:241], s[28:29], v[240:241]
	v_pk_mul_f32 v[242:243], s[28:29], v[242:243]
	v_pk_mul_f32 v[244:245], s[28:29], v[244:245]
	v_pk_mul_f32 v[246:247], s[28:29], v[246:247]
	v_pk_fma_f32 v[130:131], v[216:217], v[126:127], v[130:131]
	v_pk_fma_f32 v[132:133], v[218:219], v[128:129], v[132:133]
	v_pk_fma_f32 v[134:135], v[216:217], v[110:111], v[134:135]
	v_pk_fma_f32 v[136:137], v[218:219], v[112:113], v[136:137]
	v_pk_fma_f32 v[138:139], v[216:217], v[94:95], v[138:139]
	v_pk_fma_f32 v[140:141], v[218:219], v[96:97], v[140:141]
	v_pk_fma_f32 v[142:143], v[216:217], v[78:79], v[142:143]
	v_pk_fma_f32 v[144:145], v[218:219], v[80:81], v[144:145]
	global_store_dwordx4 v248, v[130:133], s[12:13] offset:0 sc1
	s_add_u32 s2, s12, 0x10000
	s_addc_u32 s3, s13, 0
	global_store_dwordx4 v248, v[134:137], s[2:3] offset:0 sc1
	s_add_u32 s2, s12, 0x20000
	s_addc_u32 s3, s13, 0
	global_store_dwordx4 v248, v[138:141], s[2:3] offset:0 sc1
	s_add_u32 s2, s12, 0x30000
	s_addc_u32 s3, s13, 0
	global_store_dwordx4 v248, v[142:145], s[2:3] offset:0 sc1
	global_load_dwordx4 v[130:133], v248, s[10:11] offset:512
	s_add_u32 s14, s10, 0x10000
	s_addc_u32 s15, s11, 0
	global_load_dwordx4 v[134:137], v248, s[14:15] offset:512
	s_add_u32 s14, s10, 0x20000
	s_addc_u32 s15, s11, 0
	global_load_dwordx4 v[138:141], v248, s[14:15] offset:512
	s_add_u32 s14, s10, 0x30000
	s_addc_u32 s15, s11, 0
	global_load_dwordx4 v[142:145], v248, s[14:15] offset:512
	s_waitcnt vmcnt(16)
	v_pk_fma_f32 v[146:147], v[216:217], v[62:63], v[146:147]
	v_pk_fma_f32 v[148:149], v[218:219], v[64:65], v[148:149]
	v_pk_fma_f32 v[150:151], v[216:217], v[46:47], v[150:151]
	v_pk_fma_f32 v[152:153], v[218:219], v[48:49], v[152:153]
	v_pk_fma_f32 v[154:155], v[216:217], v[30:31], v[154:155]
	v_pk_fma_f32 v[156:157], v[218:219], v[32:33], v[156:157]
	v_pk_fma_f32 v[158:159], v[216:217], v[14:15], v[158:159]
	v_pk_fma_f32 v[160:161], v[218:219], v[16:17], v[160:161]
	s_add_u32 s2, s12, 0x80000
	s_addc_u32 s3, s13, 0
	global_store_dwordx4 v248, v[146:149], s[2:3] offset:0 sc1
	s_add_u32 s2, s12, 0x90000
	s_addc_u32 s3, s13, 0
	global_store_dwordx4 v248, v[150:153], s[2:3] offset:0 sc1
	s_add_u32 s2, s12, 0xa0000
	s_addc_u32 s3, s13, 0
	global_store_dwordx4 v248, v[154:157], s[2:3] offset:0 sc1
	s_add_u32 s2, s12, 0xb0000
	s_addc_u32 s3, s13, 0
	global_store_dwordx4 v248, v[158:161], s[2:3] offset:0 sc1
	s_add_u32 s14, s10, 0x80000
	s_addc_u32 s15, s11, 0
	global_load_dwordx4 v[146:149], v248, s[14:15] offset:512
	s_add_u32 s14, s10, 0x90000
	s_addc_u32 s15, s11, 0
	global_load_dwordx4 v[150:153], v248, s[14:15] offset:512
	s_add_u32 s14, s10, 0xa0000
	s_addc_u32 s15, s11, 0
	global_load_dwordx4 v[154:157], v248, s[14:15] offset:512
	s_add_u32 s14, s10, 0xb0000
	s_addc_u32 s15, s11, 0
	global_load_dwordx4 v[158:161], v248, s[14:15] offset:512
	s_waitcnt vmcnt(20)
	v_pk_fma_f32 v[162:163], v[220:221], v[122:123], v[162:163]
	v_pk_fma_f32 v[164:165], v[222:223], v[124:125], v[164:165]
	v_pk_fma_f32 v[188:189], v[220:221], v[106:107], v[188:189]
	v_pk_fma_f32 v[190:191], v[222:223], v[108:109], v[190:191]
	v_pk_fma_f32 v[192:193], v[220:221], v[90:91], v[192:193]
	v_pk_fma_f32 v[194:195], v[222:223], v[92:93], v[194:195]
	v_pk_fma_f32 v[196:197], v[220:221], v[74:75], v[196:197]
	v_pk_fma_f32 v[198:199], v[222:223], v[76:77], v[198:199]
	global_store_dwordx4 v248, v[162:165], s[12:13] offset:64 sc1
	s_add_u32 s2, s12, 0x10000
	s_addc_u32 s3, s13, 0
	global_store_dwordx4 v248, v[188:191], s[2:3] offset:64 sc1
	s_add_u32 s2, s12, 0x20000
	s_addc_u32 s3, s13, 0
	global_store_dwordx4 v248, v[192:195], s[2:3] offset:64 sc1
	s_add_u32 s2, s12, 0x30000
	s_addc_u32 s3, s13, 0
	global_store_dwordx4 v248, v[196:199], s[2:3] offset:64 sc1
	global_load_dwordx4 v[162:165], v248, s[10:11] offset:576
	s_add_u32 s14, s10, 0x10000
	s_addc_u32 s15, s11, 0
	global_load_dwordx4 v[188:191], v248, s[14:15] offset:576
	s_add_u32 s14, s10, 0x20000
	s_addc_u32 s15, s11, 0
	global_load_dwordx4 v[192:195], v248, s[14:15] offset:576
	s_add_u32 s14, s10, 0x30000
	s_addc_u32 s15, s11, 0
	global_load_dwordx4 v[196:199], v248, s[14:15] offset:576
	s_waitcnt vmcnt(24)
	v_pk_fma_f32 v[200:201], v[220:221], v[58:59], v[200:201]
	v_pk_fma_f32 v[202:203], v[222:223], v[60:61], v[202:203]
	v_pk_fma_f32 v[204:205], v[220:221], v[42:43], v[204:205]
	v_pk_fma_f32 v[206:207], v[222:223], v[44:45], v[206:207]
	v_pk_fma_f32 v[208:209], v[220:221], v[26:27], v[208:209]
	v_pk_fma_f32 v[210:211], v[222:223], v[28:29], v[210:211]
	v_pk_fma_f32 v[212:213], v[220:221], v[10:11], v[212:213]
	v_pk_fma_f32 v[214:215], v[222:223], v[12:13], v[214:215]
	s_add_u32 s2, s12, 0x80000
	s_addc_u32 s3, s13, 0
	global_store_dwordx4 v248, v[200:203], s[2:3] offset:64 sc1
	s_add_u32 s2, s12, 0x90000
	s_addc_u32 s3, s13, 0
	global_store_dwordx4 v248, v[204:207], s[2:3] offset:64 sc1
	s_add_u32 s2, s12, 0xa0000
	s_addc_u32 s3, s13, 0
	global_store_dwordx4 v248, v[208:211], s[2:3] offset:64 sc1
	s_add_u32 s2, s12, 0xb0000
	s_addc_u32 s3, s13, 0
	global_store_dwordx4 v248, v[212:215], s[2:3] offset:64 sc1
	s_add_u32 s14, s10, 0x80000
	s_addc_u32 s15, s11, 0
	global_load_dwordx4 v[200:203], v248, s[14:15] offset:576
	s_add_u32 s14, s10, 0x90000
	s_addc_u32 s15, s11, 0
	global_load_dwordx4 v[204:207], v248, s[14:15] offset:576
	s_add_u32 s14, s10, 0xa0000
	s_addc_u32 s15, s11, 0
	global_load_dwordx4 v[208:211], v248, s[14:15] offset:576
	s_add_u32 s14, s10, 0xb0000
	s_addc_u32 s15, s11, 0
	global_load_dwordx4 v[212:215], v248, s[14:15] offset:576
	s_waitcnt vmcnt(24)
	v_pk_fma_f32 v[130:131], v[240:241], v[118:119], v[130:131]
	v_pk_fma_f32 v[132:133], v[242:243], v[120:121], v[132:133]
	v_pk_fma_f32 v[134:135], v[240:241], v[102:103], v[134:135]
	v_pk_fma_f32 v[136:137], v[242:243], v[104:105], v[136:137]
	v_pk_fma_f32 v[138:139], v[240:241], v[86:87], v[138:139]
	v_pk_fma_f32 v[140:141], v[242:243], v[88:89], v[140:141]
	v_pk_fma_f32 v[142:143], v[240:241], v[70:71], v[142:143]
	v_pk_fma_f32 v[144:145], v[242:243], v[72:73], v[144:145]
	global_store_dwordx4 v248, v[130:133], s[12:13] offset:512 sc1
	s_add_u32 s2, s12, 0x10000
	s_addc_u32 s3, s13, 0
	global_store_dwordx4 v248, v[134:137], s[2:3] offset:512 sc1
	s_add_u32 s2, s12, 0x20000
	s_addc_u32 s3, s13, 0
	global_store_dwordx4 v248, v[138:141], s[2:3] offset:512 sc1
	s_add_u32 s2, s12, 0x30000
	s_addc_u32 s3, s13, 0
	global_store_dwordx4 v248, v[142:145], s[2:3] offset:512 sc1
	s_waitcnt vmcnt(20)
	v_pk_fma_f32 v[146:147], v[240:241], v[54:55], v[146:147]
	v_pk_fma_f32 v[148:149], v[242:243], v[56:57], v[148:149]
	v_pk_fma_f32 v[150:151], v[240:241], v[38:39], v[150:151]
	v_pk_fma_f32 v[152:153], v[242:243], v[40:41], v[152:153]
	v_pk_fma_f32 v[154:155], v[240:241], v[22:23], v[154:155]
	v_pk_fma_f32 v[156:157], v[242:243], v[24:25], v[156:157]
	v_pk_fma_f32 v[158:159], v[240:241], v[6:7], v[158:159]
	v_pk_fma_f32 v[160:161], v[242:243], v[8:9], v[160:161]
	s_add_u32 s2, s12, 0x80000
	s_addc_u32 s3, s13, 0
	global_store_dwordx4 v248, v[146:149], s[2:3] offset:512 sc1
	s_add_u32 s2, s12, 0x90000
	s_addc_u32 s3, s13, 0
	global_store_dwordx4 v248, v[150:153], s[2:3] offset:512 sc1
	s_add_u32 s2, s12, 0xa0000
	s_addc_u32 s3, s13, 0
	global_store_dwordx4 v248, v[154:157], s[2:3] offset:512 sc1
	s_add_u32 s2, s12, 0xb0000
	s_addc_u32 s3, s13, 0
	global_store_dwordx4 v248, v[158:161], s[2:3] offset:512 sc1
	s_waitcnt vmcnt(16)
	v_pk_fma_f32 v[162:163], v[244:245], v[114:115], v[162:163]
	v_pk_fma_f32 v[164:165], v[246:247], v[116:117], v[164:165]
	v_pk_fma_f32 v[188:189], v[244:245], v[98:99], v[188:189]
	v_pk_fma_f32 v[190:191], v[246:247], v[100:101], v[190:191]
	v_pk_fma_f32 v[192:193], v[244:245], v[82:83], v[192:193]
	v_pk_fma_f32 v[194:195], v[246:247], v[84:85], v[194:195]
	v_pk_fma_f32 v[196:197], v[244:245], v[66:67], v[196:197]
	v_pk_fma_f32 v[198:199], v[246:247], v[68:69], v[198:199]
	global_store_dwordx4 v248, v[162:165], s[12:13] offset:576 sc1
	s_add_u32 s2, s12, 0x10000
	s_addc_u32 s3, s13, 0
	global_store_dwordx4 v248, v[188:191], s[2:3] offset:576 sc1
	s_add_u32 s2, s12, 0x20000
	s_addc_u32 s3, s13, 0
	global_store_dwordx4 v248, v[192:195], s[2:3] offset:576 sc1
	s_add_u32 s2, s12, 0x30000
	s_addc_u32 s3, s13, 0
	global_store_dwordx4 v248, v[196:199], s[2:3] offset:576 sc1
	s_waitcnt vmcnt(12)
	v_pk_fma_f32 v[200:201], v[244:245], v[50:51], v[200:201]
	v_pk_fma_f32 v[202:203], v[246:247], v[52:53], v[202:203]
	v_pk_fma_f32 v[204:205], v[244:245], v[34:35], v[204:205]
	v_pk_fma_f32 v[206:207], v[246:247], v[36:37], v[206:207]
	v_pk_fma_f32 v[208:209], v[244:245], v[18:19], v[208:209]
	v_pk_fma_f32 v[210:211], v[246:247], v[20:21], v[210:211]
	v_pk_fma_f32 v[212:213], v[244:245], v[2:3], v[212:213]
	v_pk_fma_f32 v[214:215], v[246:247], v[4:5], v[214:215]
	s_add_u32 s2, s12, 0x80000
	s_addc_u32 s3, s13, 0
	global_store_dwordx4 v248, v[200:203], s[2:3] offset:576 sc1
	s_add_u32 s2, s12, 0x90000
	s_addc_u32 s3, s13, 0
	global_store_dwordx4 v248, v[204:207], s[2:3] offset:576 sc1
	s_add_u32 s2, s12, 0xa0000
	s_addc_u32 s3, s13, 0
	global_store_dwordx4 v248, v[208:211], s[2:3] offset:576 sc1
	s_add_u32 s2, s12, 0xb0000
	s_addc_u32 s3, s13, 0
	global_store_dwordx4 v248, v[212:215], s[2:3] offset:576 sc1
	s_branch .LBB0_561
